# v56: v53 + up GEMM walks the token-tile halves in the opposite order (most recently written H rows first)
# baseline (speedup 1.0000x reference)
.LBB0_755:
	s_and_b32 s4, s52, 7
	v_readlane_b32 s5, v253, 25
	s_or_b32 s4, s4, s5
	s_mul_hi_i32 s5, s52, 0x2e8ba2e9
	s_lshr_b32 s6, s5, 31
	s_lshr_b32 s5, s5, 5
	s_add_i32 s5, s5, s6
	s_lshl_b32 s22, s4, 8
	s_ashr_i32 s4, s52, 3
	s_lshl_b32 s12, s5, 11
	s_xor_b32 s12, s12, 0x800
	s_mul_hi_i32 s5, s4, 0x2e8ba2e9
	s_lshr_b32 s6, s5, 31
	s_lshr_b32 s5, s5, 2
	s_add_i32 s5, s5, s6
	v_mov_b32_e32 v193, v234
	s_add_i32 s22, s22, s12
	s_mul_i32 s5, s5, 22
	s_sub_i32 s4, s4, s5
	v_ashrrev_i32_e32 v52, 3, v193
	v_add_u32_e32 v0, s22, v52
	s_lshl_b32 s6, s4, 8
	v_ashrrev_i32_e32 v1, 31, v0
	v_readlane_b32 s4, v252, 20
	v_lshlrev_b64 v[0:1], 11, v[0:1]
	v_add_u32_e32 v2, s6, v52
	v_lshlrev_b32_e32 v190, 4, v193
	v_readlane_b32 s5, v252, 21
	v_ashrrev_i32_e32 v3, 31, v2
	v_and_b32_e32 v200, 0x70, v190
	v_lshl_add_u64 v[0:1], s[4:5], 0, v[0:1]
	v_lshlrev_b64 v[32:33], 11, v[2:3]
	v_lshl_add_u64 v[36:37], v[0:1], 0, v[200:201]
	v_lshl_add_u64 v[2:3], s[2:3], 0, v[32:33]
	v_add_co_u32_e32 v38, vcc, s25, v36
	v_lshl_add_u64 v[34:35], v[2:3], 0, v[200:201]
	s_nop 0
	v_addc_co_u32_e32 v39, vcc, 0, v37, vcc
	v_add_co_u32_e32 v40, vcc, s25, v34
	v_ashrrev_i32_e32 v18, 7, v193
	s_nop 0
	v_addc_co_u32_e32 v41, vcc, 0, v35, vcc
	s_movk_i32 s0, 0x1600
	v_add_co_u32_e32 v42, vcc, s47, v36
	v_mul_lo_u32 v16, v18, s0
	s_nop 0
	v_addc_co_u32_e32 v43, vcc, 0, v37, vcc
	v_ashrrev_i32_e32 v17, 31, v16
	v_lshl_add_u64 v[16:17], v[16:17], 2, s[38:39]
	v_cmp_gt_i32_e32 vcc, 3, v18
	v_mov_b32_e32 v18, s40
	v_mov_b32_e32 v19, s41
	v_cndmask_b32_e32 v16, v18, v16, vcc
	v_lshlrev_b32_e32 v18, 1, v193
	v_cndmask_b32_e32 v17, v19, v17, vcc
	v_and_b32_e32 v19, 0xc0, v18
	v_or_b32_e32 v19, s6, v19
	v_and_b32_e32 v18, 30, v18
	v_bfe_i32 v20, v193, 4, 1
	s_movk_i32 s0, 0xb00
	v_ashrrev_i32_e32 v19, 1, v19
	v_and_or_b32 v18, v20, s0, v18
	v_add_u32_e32 v18, v18, v19
	v_ashrrev_i32_e32 v19, 31, v18
	v_lshl_add_u64 v[16:17], v[18:19], 2, v[16:17]
	v_add_co_u32_e32 v46, vcc, s47, v34
	global_load_dwordx4 v[0:3], v[36:37], off
	global_load_dwordx4 v[4:7], v[34:35], off
	global_load_dwordx4 v[8:11], v[38:39], off
	global_load_dwordx4 v[12:15], v[40:41], off
	global_load_dwordx2 v[44:45], v[16:17], off
	v_addc_co_u32_e32 v47, vcc, 0, v35, vcc
	s_mov_b32 s1, 0x60000
	v_add_co_u32_e32 v48, vcc, s1, v36
	global_load_dwordx4 v[16:19], v[42:43], off
	global_load_dwordx4 v[20:23], v[46:47], off
	v_addc_co_u32_e32 v49, vcc, 0, v37, vcc
	v_add_co_u32_e32 v50, vcc, s1, v34
	v_lshlrev_b32_e32 v53, 5, v52
	s_nop 0
	v_addc_co_u32_e32 v51, vcc, 0, v35, vcc
	global_load_dwordx4 v[24:27], v[48:49], off
	global_load_dwordx4 v[28:31], v[50:51], off
	v_and_b32_e32 v54, 0x80, v52
	v_lshrrev_b32_e32 v55, 2, v52
	v_and_b32_e32 v53, 0x60, v53
	v_and_or_b32 v54, v55, 31, v54
	v_or_b32_e32 v55, v54, v53
	v_mad_u32_u24 v194, v55, s24, v200
	v_add_u32_e32 v55, 64, v52
	s_movk_i32 s1, 0x80
	v_and_b32_e32 v56, 0x80, v55
	v_bfe_u32 v55, v55, 2, 5
	v_bitop3_b32 v54, v54, s1, v53 bitop3:0x36
	v_or3_b32 v55, v56, v55, v53
	v_mad_u32_u24 v196, v54, s24, v200
	v_add_u32_e32 v54, 0xc0, v52
	v_mad_u32_u24 v195, v55, s24, v200
	v_and_b32_e32 v55, 0x80, v54
	v_bfe_u32 v54, v54, 2, 5
	v_or3_b32 v53, v55, v54, v53
	v_mad_u32_u24 v197, v53, s24, v200
	v_lshl_add_u32 v53, v193, 3, 0
	s_and_b32 s4, s51, 7
	v_add_u32_e32 v53, 0x24000, v53
	s_lshl_b32 s13, s4, 8
	v_mad_u64_u32 v[184:185], s[4:5], v52, s24, v[200:201]
	v_readfirstlane_b32 s7, v193
	s_ashr_i32 s34, s7, 6
	s_lshl_b32 s4, s34, 7
	v_and_b32_e32 v191, 31, v193
	s_and_b32 s36, s4, 0x80
	s_ashr_i32 s17, s7, 1
	s_and_b32 s7, s17, 0xffffffc0
	s_or_b32 s4, s13, s12
	s_add_i32 s4, s4, s15
	v_bfe_u32 v192, v193, 5, 1
	v_or_b32_e32 v32, v32, v200
	s_mov_b32 s0, 0x60000
	s_mov_b32 s16, 2
	s_mov_b32 s35, 0
	v_lshlrev_b32_e32 v198, 4, v192
	v_lshl_add_u64 v[186:187], s[30:31], 0, v[32:33]
	s_waitcnt vmcnt(4)
	ds_write_b64 v53, v[44:45]
	v_add_u32_e32 v45, 0, v194
	v_add_u32_e32 v44, 0, v184
	ds_write_b128 v45, v[0:3]
	ds_write_b128 v44, v[4:7] offset:36864
	v_add_u32_e32 v0, 0, v195
	ds_write_b128 v0, v[8:11]
	ds_write_b128 v44, v[12:15] offset:46080
	v_add_u32_e32 v0, 0, v196
	s_waitcnt vmcnt(3)
	ds_write_b128 v0, v[16:19]
	s_waitcnt vmcnt(2)
	ds_write_b128 v44, v[20:23] offset:55296
	v_add_u32_e32 v0, 0, v197
	s_waitcnt vmcnt(1)
	ds_write_b128 v0, v[24:27]
	s_waitcnt vmcnt(0)
	ds_write_b128 v44, v[28:31] offset:64512
	s_waitcnt lgkmcnt(0)
	s_barrier
	global_load_dwordx4 v[128:131], v[36:37], off offset:128
	global_load_dwordx4 v[132:135], v[34:35], off offset:128
	global_load_dwordx4 v[136:139], v[38:39], off offset:128
	global_load_dwordx4 v[140:143], v[40:41], off offset:128
	global_load_dwordx4 v[144:147], v[42:43], off offset:128
	global_load_dwordx4 v[148:151], v[46:47], off offset:128
	global_load_dwordx4 v[152:155], v[48:49], off offset:128
	global_load_dwordx4 v[156:159], v[50:51], off offset:128
	v_or_b32_e32 v0, s36, v191
	v_mul_u32_u24_e32 v185, 0x90, v0
	v_or_b32_e32 v0, s7, v191
	v_mul_lo_u32 v199, v0, s24
	v_add_u32_e32 v0, s4, v52
	v_ashrrev_i32_e32 v1, 31, v0
	v_lshlrev_b64 v[0:1], 11, v[0:1]
	v_or_b32_e32 v0, v0, v200
	v_lshl_add_u64 v[188:189], s[10:11], 0, v[0:1]
	v_mov_b32_e32 v0, 0
	s_mov_b64 s[4:5], 0
	v_mov_b32_e32 v1, v0
	v_mov_b32_e32 v2, v0
	v_mov_b32_e32 v3, v0
	v_mov_b32_e32 v4, v0
	v_mov_b32_e32 v5, v0
	v_mov_b32_e32 v6, v0
	v_mov_b32_e32 v7, v0
	v_mov_b32_e32 v8, v0
	v_mov_b32_e32 v9, v0
	v_mov_b32_e32 v10, v0
	v_mov_b32_e32 v11, v0
	v_mov_b32_e32 v12, v0
	v_mov_b32_e32 v13, v0
	v_mov_b32_e32 v14, v0
	v_mov_b32_e32 v15, v0
	v_mov_b32_e32 v16, v0
	v_mov_b32_e32 v17, v0
	v_mov_b32_e32 v18, v0
	v_mov_b32_e32 v19, v0
	v_mov_b32_e32 v20, v0
	v_mov_b32_e32 v21, v0
	v_mov_b32_e32 v22, v0
	v_mov_b32_e32 v23, v0
	v_mov_b32_e32 v24, v0
	v_mov_b32_e32 v25, v0
	v_mov_b32_e32 v26, v0
	v_mov_b32_e32 v27, v0
	v_mov_b32_e32 v28, v0
	v_mov_b32_e32 v29, v0
	v_mov_b32_e32 v30, v0
	v_mov_b32_e32 v31, v0
	v_mov_b32_e32 v32, v0
	v_mov_b32_e32 v33, v0
	v_mov_b32_e32 v34, v0
	v_mov_b32_e32 v35, v0
	v_mov_b32_e32 v36, v0
	v_mov_b32_e32 v37, v0
	v_mov_b32_e32 v38, v0
	v_mov_b32_e32 v39, v0
	v_mov_b32_e32 v40, v0
	v_mov_b32_e32 v41, v0
	v_mov_b32_e32 v42, v0
	v_mov_b32_e32 v43, v0
	v_mov_b32_e32 v44, v0
	v_mov_b32_e32 v45, v0
	v_mov_b32_e32 v46, v0
	v_mov_b32_e32 v47, v0
	v_mov_b32_e32 v64, v0
	v_mov_b32_e32 v65, v0
	v_mov_b32_e32 v66, v0
	v_mov_b32_e32 v67, v0
	v_mov_b32_e32 v68, v0
	v_mov_b32_e32 v69, v0
	v_mov_b32_e32 v70, v0
	v_mov_b32_e32 v71, v0
	v_mov_b32_e32 v72, v0
	v_mov_b32_e32 v73, v0
	v_mov_b32_e32 v74, v0
	v_mov_b32_e32 v75, v0
	v_mov_b32_e32 v76, v0
	v_mov_b32_e32 v77, v0
	v_mov_b32_e32 v78, v0
	v_mov_b32_e32 v79, v0
	v_mov_b32_e32 v48, v0
	v_mov_b32_e32 v49, v0
	v_mov_b32_e32 v50, v0
	v_mov_b32_e32 v51, v0
	v_mov_b32_e32 v52, v0
	v_mov_b32_e32 v53, v0
	v_mov_b32_e32 v54, v0
	v_mov_b32_e32 v55, v0
	v_mov_b32_e32 v56, v0
	v_mov_b32_e32 v57, v0
	v_mov_b32_e32 v58, v0
	v_mov_b32_e32 v59, v0
	v_mov_b32_e32 v60, v0
	v_mov_b32_e32 v61, v0
	v_mov_b32_e32 v62, v0
	v_mov_b32_e32 v63, v0
	v_mov_b32_e32 v80, v0
	v_mov_b32_e32 v81, v0
	v_mov_b32_e32 v82, v0
	v_mov_b32_e32 v83, v0
	v_mov_b32_e32 v84, v0
	v_mov_b32_e32 v85, v0
	v_mov_b32_e32 v86, v0
	v_mov_b32_e32 v87, v0
	v_mov_b32_e32 v88, v0
	v_mov_b32_e32 v89, v0
	v_mov_b32_e32 v90, v0
	v_mov_b32_e32 v91, v0
	v_mov_b32_e32 v92, v0
	v_mov_b32_e32 v93, v0
	v_mov_b32_e32 v94, v0
	v_mov_b32_e32 v95, v0
	v_mov_b32_e32 v96, v0
	v_mov_b32_e32 v97, v0
	v_mov_b32_e32 v98, v0
	v_mov_b32_e32 v99, v0
	v_mov_b32_e32 v100, v0
	v_mov_b32_e32 v101, v0
	v_mov_b32_e32 v102, v0
	v_mov_b32_e32 v103, v0
	v_mov_b32_e32 v104, v0
	v_mov_b32_e32 v105, v0
	v_mov_b32_e32 v106, v0
	v_mov_b32_e32 v107, v0
	v_mov_b32_e32 v108, v0
	v_mov_b32_e32 v109, v0
	v_mov_b32_e32 v110, v0
	v_mov_b32_e32 v111, v0
	v_mov_b32_e32 v112, v0
	v_mov_b32_e32 v113, v0
	v_mov_b32_e32 v114, v0
	v_mov_b32_e32 v115, v0
	v_mov_b32_e32 v116, v0
	v_mov_b32_e32 v117, v0
	v_mov_b32_e32 v118, v0
	v_mov_b32_e32 v119, v0
	v_mov_b32_e32 v120, v0
	v_mov_b32_e32 v121, v0
	v_mov_b32_e32 v122, v0
	v_mov_b32_e32 v123, v0
	v_mov_b32_e32 v124, v0
	v_mov_b32_e32 v125, v0
	v_mov_b32_e32 v126, v0
	v_mov_b32_e32 v127, v0
	v_readfirstlane_b32 s92, v188
	v_readfirstlane_b32 s93, v189
	v_readfirstlane_b32 s94, v186
	v_readfirstlane_b32 s95, v187
	s_nop 1
	v_subrev_u32_e32 v248, s92, v188
	v_add_u32_e32 v249, 0x20000, v248
	v_add_u32_e32 v250, 0x40000, v248
	v_add_u32_e32 v251, 0x60000, v248
	s_add_u32 s92, s92, 0x6d00000
	s_addc_u32 s93, s93, 0
	s_add_u32 s94, s94, 0x900000
	s_addc_u32 s95, s95, 0
	s_branch .LBB0_758
